# v33 + acquire-side L1 invalidate hoisted before the row-panel counter polling (4 hand-off sites)
# speedup vs baseline: 1.0378x; 1.0004x over previous
.LBB0_587:
	s_andn2_b64 vcc, exec, s[4:5]
	s_cbranch_vccnz .LBB0_608
	v_readlane_b32 s4, v249, 7
	s_cmp_gt_u32 s4, 63
	s_cbranch_scc1 .LBB0_607
	buffer_inv sc1
	s_lshl_b32 s4, s2, 3
	s_add_i32 s4, s3, s4
	s_min_i32 s4, s4, 0x5000
	s_add_i32 s4, s4, -1
	s_ashr_i32 s3, s3, 8
	s_ashr_i32 s16, s4, 8
	s_cmp_gt_i32 s3, s16
	s_cbranch_scc1 .LBB0_606
	s_add_u32 s17, s56, 0xc0000
	s_addc_u32 s18, s57, 0
	v_cmp_eq_u32_e64 s[4:5], 0, v204
	v_mov_b32_e32 v1, 0
	s_branch .LBB0_593

.LBB0_606:
	s_waitcnt vmcnt(0)
	s_waitcnt vmcnt(0)

.LBB0_855:
	s_andn2_b64 vcc, exec, s[0:1]
	s_cbranch_vccnz .LBB0_876
	v_readlane_b32 s0, v249, 7
	s_cmp_gt_u32 s0, 63
	s_cbranch_scc1 .LBB0_875
	buffer_inv sc1
	s_lshl_b32 s0, s2, 3
	s_add_i32 s0, s3, s0
	s_min_i32 s0, s0, 0x5000
	s_add_i32 s0, s0, -1
	s_ashr_i32 s3, s3, 8
	s_ashr_i32 s14, s0, 8
	s_cmp_gt_i32 s3, s14
	s_cbranch_scc1 .LBB0_874
	s_add_u32 s15, s56, 0xc5000
	s_addc_u32 s16, s57, 0
	v_cmp_eq_u32_e64 s[4:5], 0, v204
	v_mov_b32_e32 v1, 0
	s_branch .LBB0_861

.LBB0_1462:
	s_andn2_b64 vcc, exec, s[0:1]
	s_cbranch_vccnz .LBB0_1483
	v_readlane_b32 s0, v249, 7
	s_cmp_gt_u32 s0, 63
	s_cbranch_scc1 .LBB0_1482
	buffer_inv sc1
	s_lshl_b32 s0, s2, 3
	s_add_i32 s0, s3, s0
	s_min_i32 s0, s0, 0x5000
	s_add_i32 s0, s0, -1
	s_ashr_i32 s3, s3, 8
	s_ashr_i32 s12, s0, 8
	s_cmp_gt_i32 s3, s12
	s_cbranch_scc1 .LBB0_1481
	s_add_u32 s13, s56, 0xca000
	s_addc_u32 s16, s57, 0
	v_cmp_eq_u32_e64 s[4:5], 0, v204
	v_mov_b32_e32 v1, 0
	s_branch .LBB0_1468

.LBB0_1729:
	s_andn2_b64 vcc, exec, s[0:1]
	s_cbranch_vccnz .LBB0_1750
	v_readlane_b32 s0, v249, 7
	s_cmp_gt_u32 s0, 63
	s_cbranch_scc1 .LBB0_1749
	buffer_inv sc1
	s_lshl_b32 s0, s10, 3
	s_add_i32 s0, s2, s0
	s_min_i32 s0, s0, 0x5000
	s_add_i32 s0, s0, -1
	s_ashr_i32 s11, s2, 8
	s_ashr_i32 s12, s0, 8
	s_cmp_gt_i32 s11, s12
	s_cbranch_scc1 .LBB0_1748
	s_add_u32 s13, s56, 0xcf000
	s_addc_u32 s14, s57, 0
	v_cmp_eq_u32_e64 s[0:1], 0, v204
	v_mov_b32_e32 v0, 0
	s_branch .LBB0_1735
